# uprep (hyena short conv): neighbour ushort loads no longer wait one by one, conv weights loaded together with the token data (one memory round trip per step instead of seven)
# speedup vs baseline: 1.0017x; 1.0017x over previous
; DEVI void uprep_phase(const Params& p, int l) {
;     ...
;   auto ld = [&](In& q, const int idx) {
;     const int c = idx / NCH, ck = idx % NCH, row = ck * 8;
;     int t, Lseq; if (row < TL) { t = row & 4095; Lseq = SEQ; } else { t = (row - TL) & 255; Lseq = CTXL; }
; #pragma unroll
;     for (int k = 0; k < 3; ++k) {
;       const u16* src = PT + (size_t)(512 + k * 256 + c) * T + row;
;       q.v[k] = *(const bf16x8*)src;
;       q.pv[k] = t > 0 ? src[-1] : (u16)0;
;       q.nx[k] = (t + 8 < Lseq) ? src[8] : (u16)0;
;     }
;   };
;     ...
;       const float w0 = p.in[18][(l * 3 + 0) * 768 + col], w1 = p.in[18][(l * 3 + 1) * 768 + col], w2 = p.in[18][(l * 3 + 2) * 768 + col], bb = p.in[19][l * 768 + col];
.LBB0_1393:
	v_mul_hi_i32 v12, v30, s22
	v_lshrrev_b32_e32 v13, 31, v12
	v_ashrrev_i32_e32 v12, 11, v12
	v_add_u32_e32 v26, v12, v13
	v_mul_i32_i24_e32 v14, 0x1100, v26
	v_lshlrev_b32_e32 v12, 3, v14
	v_sub_u32_e32 v24, v31, v12
	v_add_u32_e32 v12, 0x200, v26
	v_mul_hi_i32_i24_e32 v13, 0x11000, v12
	v_mul_i32_i24_e32 v12, 0x11000, v12
	v_ashrrev_i32_e32 v25, 31, v24
	v_lshl_add_u64 v[12:13], s[60:61], 0, v[12:13]
	v_lshl_add_u64 v[12:13], v[24:25], 1, v[12:13]
	global_load_dwordx4 v[20:23], v[12:13], off
	v_sub_u32_e32 v14, v30, v14
	v_cmp_gt_i32_e64 s[6:7], s83, v14
	v_mov_b32_e32 v27, 0
	v_mov_b32_e32 v44, 0
	v_cndmask_b32_e64 v14, v242, v243, s[6:7]
	v_and_b32_e32 v14, v14, v24
	v_cmp_ne_u32_e32 vcc, 0, v14
	s_and_saveexec_b64 s[8:9], vcc
	s_cbranch_execz .LBB0_1395
	global_load_ushort v44, v[12:13], off offset:-2
.LBB0_1395:
	s_or_b64 exec, exec, s[8:9]
	v_cndmask_b32_e64 v15, v244, v231, s[6:7]
	v_add_u32_e32 v14, 8, v14
	v_cmp_lt_u32_e64 s[6:7], v14, v15
	s_and_saveexec_b64 s[8:9], s[6:7]
	s_cbranch_execz .LBB0_1397
	global_load_ushort v27, v[12:13], off offset:16
.LBB0_1397:
	s_or_b64 exec, exec, s[8:9]
	v_add_u32_e32 v12, 0x300, v26
	v_mul_hi_i32_i24_e32 v13, 0x11000, v12
	v_mul_i32_i24_e32 v12, 0x11000, v12
	v_lshl_add_u64 v[12:13], s[60:61], 0, v[12:13]
	v_lshl_add_u64 v[12:13], v[24:25], 1, v[12:13]
	global_load_dwordx4 v[16:19], v[12:13], off
	v_mov_b32_e32 v54, 0
	v_mov_b32_e32 v51, 0
	s_and_saveexec_b64 s[8:9], vcc
	s_cbranch_execz .LBB0_1399
	global_load_ushort v51, v[12:13], off offset:-2
.LBB0_1399:
	s_or_b64 exec, exec, s[8:9]
	s_and_saveexec_b64 s[8:9], s[6:7]
	s_cbranch_execz .LBB0_1401
	global_load_ushort v54, v[12:13], off offset:16
.LBB0_1401:
	s_or_b64 exec, exec, s[8:9]
	v_add_u32_e32 v12, 0x400, v26
	v_mul_hi_i32_i24_e32 v13, 0x11000, v12
	v_mul_i32_i24_e32 v12, 0x11000, v12
	v_lshl_add_u64 v[12:13], s[60:61], 0, v[12:13]
	v_lshl_add_u64 v[28:29], v[24:25], 1, v[12:13]
	global_load_dwordx4 v[12:15], v[28:29], off
	v_mov_b32_e32 v41, 0
	v_mov_b32_e32 v42, 0
	s_and_saveexec_b64 s[8:9], vcc
	s_cbranch_execz .LBB0_1403
	global_load_ushort v42, v[28:29], off offset:-2
.LBB0_1403:
	s_or_b64 exec, exec, s[8:9]
	s_and_saveexec_b64 s[8:9], s[6:7]
	s_cbranch_execz .LBB0_1405
	global_load_ushort v41, v[28:29], off offset:16
.LBB0_1405:
	s_or_b64 exec, exec, s[8:9]
	v_readlane_b32 s24, v252, 50
	v_readlane_b32 s25, v252, 51
	v_readlane_b32 s26, v252, 52
	v_readlane_b32 s27, v252, 53
	v_add_u32_e32 v106, s0, v26
	v_ashrrev_i32_e32 v107, 31, v106
	v_lshl_add_u64 v[98:99], v[106:107], 2, s[24:25]
	v_add_u32_e32 v106, s2, v106
	v_ashrrev_i32_e32 v107, 31, v106
	v_lshl_add_u64 v[100:101], v[106:107], 2, s[26:27]
	v_add_u32_e32 v106, s1, v26
	v_ashrrev_i32_e32 v107, 31, v106
	v_lshl_add_u64 v[102:103], v[106:107], 2, s[24:25]
	v_mov_b32_e32 v106, v26
	v_ashrrev_i32_e32 v107, 31, v26
	v_lshl_add_u64 v[106:107], v[106:107], 0, s[10:11]
	v_lshl_add_u64 v[104:105], v[106:107], 2, s[24:25]
	global_load_dword v74, v[98:99], off
	global_load_dword v75, v[98:99], off offset:3072
	global_load_dword v76, v[100:101], off
	global_load_dword v77, v[102:103], off
	global_load_dword v78, v[98:99], off offset:1024
	global_load_dword v79, v[104:105], off offset:1024
	global_load_dword v80, v[102:103], off offset:1024
	global_load_dword v81, v[100:101], off offset:1024
	global_load_dword v82, v[98:99], off offset:2048
	global_load_dword v83, v[104:105], off offset:2048
	global_load_dword v84, v[102:103], off offset:2048
	global_load_dword v85, v[100:101], off offset:2048
	v_readlane_b32 s6, v255, 17
	s_nop 1
	v_add_u32_e32 v38, s6, v30
	v_mul_hi_i32 v28, v38, s22
	v_cmp_gt_i32_e32 vcc, s19, v38
	v_lshrrev_b32_e32 v39, 31, v28
	v_ashrrev_i32_e32 v40, 11, v28
	s_and_saveexec_b64 s[14:15], vcc
	s_cbranch_execz .LBB0_1419
	v_add_u32_e32 v28, v40, v39
	v_add_u32_e32 v106, s0, v28
	v_ashrrev_i32_e32 v107, 31, v106
	v_lshl_add_u64 v[98:99], v[106:107], 2, s[24:25]
	v_add_u32_e32 v106, s2, v106
	v_ashrrev_i32_e32 v107, 31, v106
	v_lshl_add_u64 v[100:101], v[106:107], 2, s[26:27]
	v_add_u32_e32 v106, s1, v28
	v_ashrrev_i32_e32 v107, 31, v106
	v_lshl_add_u64 v[102:103], v[106:107], 2, s[24:25]
	v_mov_b32_e32 v106, v28
	v_ashrrev_i32_e32 v107, 31, v28
	v_lshl_add_u64 v[106:107], v[106:107], 0, s[10:11]
	v_lshl_add_u64 v[104:105], v[106:107], 2, s[24:25]
	global_load_dword v86, v[98:99], off
	global_load_dword v87, v[98:99], off offset:3072
	global_load_dword v88, v[100:101], off
	global_load_dword v89, v[102:103], off
	global_load_dword v90, v[98:99], off offset:1024
	global_load_dword v91, v[104:105], off offset:1024
	global_load_dword v92, v[102:103], off offset:1024
	global_load_dword v93, v[100:101], off offset:1024
	global_load_dword v94, v[98:99], off offset:2048
	global_load_dword v95, v[104:105], off offset:2048
	global_load_dword v96, v[102:103], off offset:2048
	global_load_dword v97, v[100:101], off offset:2048
	v_mul_i32_i24_e32 v0, 0x1100, v28
	v_sub_u32_e32 v6, v38, v0
	v_add_u32_e32 v0, 0x200, v28
	v_lshlrev_b32_e32 v8, 3, v6
	v_mul_hi_i32_i24_e32 v1, 0x11000, v0
	v_mul_i32_i24_e32 v0, 0x11000, v0
	v_ashrrev_i32_e32 v9, 31, v8
	v_lshl_add_u64 v[0:1], s[60:61], 0, v[0:1]
	v_lshl_add_u64 v[4:5], v[8:9], 1, v[0:1]
	global_load_dwordx4 v[0:3], v[4:5], off
	v_cmp_gt_i32_e64 s[8:9], s83, v6
	v_mov_b32_e32 v33, 0
	v_mov_b32_e32 v32, 0
	v_cndmask_b32_e64 v6, v242, v243, s[8:9]
	v_and_b32_e32 v6, v6, v8
	v_cmp_ne_u32_e64 s[6:7], 0, v6
	s_and_saveexec_b64 s[16:17], s[6:7]
	s_cbranch_execz .LBB0_1408
	global_load_ushort v32, v[4:5], off offset:-2

; DEVI unsigned pk_bf16(float lo, float hi) { unsigned r; asm volatile("v_cvt_pk_bf16_f32 %0, %1, %2" : "=v"(r) : "v"(lo), "v"(hi)); return r; }
; DEVI float bf2f(u16 h) { return __uint_as_float(((unsigned)h) << 16); }
; DEVI void uprep_phase(const Params& p, int l) {
;     ...
;   auto fin = [&](const In& q, const int idx) {
;     const int c = idx / NCH, ck = idx % NCH, row = ck * 8;
;     float o[3][8];
; #pragma unroll
;     for (int k = 0; k < 3; ++k) {
;       const int col = k * 256 + c;
;       float x[10];
;       x[0] = bf2f(q.pv[k]); x[9] = bf2f(q.nx[k]);
; #pragma unroll
;       for (int e = 0; e < 8; ++e) x[e + 1] = bf2f((u16)q.v[k][e]);
;       const float w0 = p.in[18][(l * 3 + 0) * 768 + col], w1 = p.in[18][(l * 3 + 1) * 768 + col], w2 = p.in[18][(l * 3 + 2) * 768 + col], bb = p.in[19][l * 768 + col];
; #pragma unroll
;       for (int e = 0; e < 8; ++e) o[k][e] = bb + w0 * x[e] + w1 * x[e + 1] + w2 * x[e + 2];
;     }
;     uint4 uo, xo;
;     uo.x = pk_bf16(o[1][0] * o[2][0], o[1][1] * o[2][1]); uo.y = pk_bf16(o[1][2] * o[2][2], o[1][3] * o[2][3]);
;     uo.z = pk_bf16(o[1][4] * o[2][4], o[1][5] * o[2][5]); uo.w = pk_bf16(o[1][6] * o[2][6], o[1][7] * o[2][7]);
;     xo.x = pk_bf16(o[0][0], o[0][1]); xo.y = pk_bf16(o[0][2], o[0][3]); xo.z = pk_bf16(o[0][4], o[0][5]); xo.w = pk_bf16(o[0][6], o[0][7]);
;     *(uint4*)(UT + (size_t)c * T + row) = uo;
;     *(uint4*)(X0T + (size_t)c * T + row) = xo;
.LBB0_1419:
	s_or_b64 exec, exec, s[14:15]
	s_waitcnt vmcnt(0)
	v_lshlrev_b32_e32 v44, 16, v44
	v_lshlrev_b32_e32 v27, 16, v27
	v_lshlrev_b32_e32 v51, 16, v51
	v_lshlrev_b32_e32 v54, 16, v54
	v_lshlrev_b32_e32 v42, 16, v42
	v_lshlrev_b32_e32 v41, 16, v41
	v_lshlrev_b32_e32 v45, 16, v20
	v_and_b32_e32 v46, 0xffff0000, v20
	v_add_u32_e32 v20, s0, v26
	v_readlane_b32 s36, v252, 46
	v_lshlrev_b32_e32 v47, 16, v21
	v_and_b32_e32 v48, 0xffff0000, v21
	v_ashrrev_i32_e32 v21, 31, v20
	v_readlane_b32 s40, v252, 50
	v_readlane_b32 s41, v252, 51
	v_readlane_b32 s42, v252, 52
	v_readlane_b32 s43, v252, 53
	v_lshl_add_u64 v[28:29], v[20:21], 2, s[40:41]
	v_add_u32_e32 v20, s2, v20
	v_ashrrev_i32_e32 v21, 31, v20
	v_lshlrev_b32_e32 v49, 16, v22
	v_and_b32_e32 v50, 0xffff0000, v22
	v_add_u32_e32 v22, s1, v26
	v_lshl_add_u64 v[20:21], v[20:21], 2, s[42:43]
	v_lshlrev_b32_e32 v52, 16, v23
	v_and_b32_e32 v53, 0xffff0000, v23
	v_mov_b32_e32 v55, v74
	v_mov_b32_e32 v56, v75
	v_ashrrev_i32_e32 v23, 31, v22
	v_mov_b32_e32 v43, v76
	v_lshl_add_u64 v[22:23], v[22:23], 2, s[40:41]
	v_mov_b32_e32 v57, v77
	v_mov_b32_e32 v63, v78
	s_waitcnt vmcnt(6)
	v_and_b32_e32 v58, 0xffff0000, v18
	v_lshlrev_b32_e32 v59, 16, v19
	v_and_b32_e32 v62, 0xffff0000, v19
	v_readlane_b32 s6, v254, 6
	v_readlane_b32 s7, v254, 7
	v_lshlrev_b64 v[24:25], 1, v[24:25]
	v_readlane_b32 s37, v252, 47
	v_readlane_b32 s38, v252, 48
	v_readlane_b32 s39, v252, 49
	v_readlane_b32 s44, v252, 54
	v_readlane_b32 s45, v252, 55
	v_readlane_b32 s46, v252, 56
	v_readlane_b32 s47, v252, 57
	v_readlane_b32 s48, v252, 58
	v_readlane_b32 s49, v252, 59
	v_readlane_b32 s50, v252, 60
	v_readlane_b32 s51, v252, 61
	s_waitcnt vmcnt(2)
	v_fma_f32 v44, v44, v55, v43
	v_fmac_f32_e32 v44, v56, v45
	v_fma_f32 v45, v55, v45, v43
	s_waitcnt vmcnt(1)
	v_fmac_f32_e32 v44, v57, v46
	v_fmac_f32_e32 v45, v56, v46
	v_fma_f32 v46, v55, v46, v43
	v_fmac_f32_e32 v45, v57, v47
	v_fmac_f32_e32 v46, v56, v47
	v_fma_f32 v47, v55, v47, v43
	v_fmac_f32_e32 v46, v57, v48
	v_fmac_f32_e32 v47, v56, v48
	v_fma_f32 v48, v55, v48, v43
	v_fmac_f32_e32 v47, v57, v49
	v_fmac_f32_e32 v48, v56, v49
	v_fma_f32 v49, v55, v49, v43
	v_fmac_f32_e32 v48, v57, v50
	v_fmac_f32_e32 v49, v56, v50
	v_fma_f32 v50, v55, v50, v43
	v_fmac_f32_e32 v43, v55, v52
	v_fmac_f32_e32 v43, v56, v53
	v_fmac_f32_e32 v50, v56, v52
	v_fmac_f32_e32 v43, v27, v57
	v_ashrrev_i32_e32 v27, 31, v26
	v_fmac_f32_e32 v49, v57, v52
	v_fmac_f32_e32 v50, v57, v53
	v_lshlrev_b32_e32 v52, 16, v16
	v_and_b32_e32 v53, 0xffff0000, v16
	v_lshlrev_b32_e32 v55, 16, v17
	v_and_b32_e32 v56, 0xffff0000, v17
	v_lshl_add_u64 v[16:17], v[26:27], 0, s[10:11]
	v_lshl_add_u64 v[60:61], v[16:17], 2, s[40:41]
	v_mov_b32_e32 v64, v79
	v_mov_b32_e32 v65, v80
	v_mov_b32_e32 v16, v81
	v_lshlrev_b32_e32 v57, 16, v18
	s_waitcnt vmcnt(0)
	v_fma_f32 v17, v51, v63, v16
	v_fmac_f32_e32 v17, v64, v52
	v_fma_f32 v18, v63, v52, v16
	v_fmac_f32_e32 v17, v65, v53
	v_fmac_f32_e32 v18, v64, v53
	v_fma_f32 v19, v63, v53, v16
	v_fma_f32 v27, v63, v55, v16
	v_fma_f32 v51, v63, v56, v16
	v_fma_f32 v52, v63, v57, v16
	v_fma_f32 v53, v63, v58, v16
	v_fmac_f32_e32 v16, v63, v59
	v_fmac_f32_e32 v19, v64, v55
	v_fmac_f32_e32 v27, v64, v56
	v_fmac_f32_e32 v51, v64, v57
	v_fmac_f32_e32 v52, v64, v58
	v_fmac_f32_e32 v16, v64, v62
	v_fmac_f32_e32 v18, v65, v55
	v_fmac_f32_e32 v19, v65, v56
	v_fmac_f32_e32 v27, v65, v57
	v_fmac_f32_e32 v51, v65, v58
	v_fmac_f32_e32 v52, v65, v59
	v_fmac_f32_e32 v53, v64, v59
	v_fmac_f32_e32 v16, v54, v65
	v_lshlrev_b32_e32 v59, 16, v12
	v_and_b32_e32 v58, 0xffff0000, v12
	v_lshlrev_b32_e32 v57, 16, v13
	v_and_b32_e32 v56, 0xffff0000, v13
	v_lshlrev_b32_e32 v55, 16, v14
	v_and_b32_e32 v54, 0xffff0000, v14
	v_lshlrev_b32_e32 v13, 16, v15
	v_and_b32_e32 v12, 0xffff0000, v15
	v_mov_b32_e32 v15, v82
	v_mov_b32_e32 v14, v83
	s_nop 0
	v_mov_b32_e32 v22, v84
	s_nop 0
	v_mov_b32_e32 v20, v85
	v_fmac_f32_e32 v53, v65, v62
	s_waitcnt vmcnt(0)
	v_fma_f32 v29, v15, v57, v20
	v_fma_f32 v21, v42, v15, v20
	v_fmac_f32_e32 v29, v14, v56
	v_fma_f32 v42, v15, v56, v20
	v_fmac_f32_e32 v29, v22, v55
	v_fmac_f32_e32 v42, v14, v55
	v_fma_f32 v55, v15, v55, v20
	v_fma_f32 v23, v15, v59, v20
	v_fma_f32 v28, v15, v58, v20
	v_fmac_f32_e32 v42, v22, v54
	v_fmac_f32_e32 v55, v14, v54
	v_fma_f32 v54, v15, v54, v20
	v_fmac_f32_e32 v20, v15, v13
	v_fmac_f32_e32 v21, v14, v59
	v_fmac_f32_e32 v23, v14, v58
	v_fmac_f32_e32 v20, v14, v12
	v_fmac_f32_e32 v21, v22, v58
	v_fmac_f32_e32 v23, v22, v57
	v_fmac_f32_e32 v28, v14, v57
	v_fmac_f32_e32 v54, v14, v13
	v_fmac_f32_e32 v20, v41, v22
	v_fmac_f32_e32 v28, v22, v56
	v_fmac_f32_e32 v55, v22, v13
	v_fmac_f32_e32 v54, v22, v12
	v_mul_f32_e32 v12, v17, v21
	v_mul_f32_e32 v13, v18, v23
	v_mul_f32_e32 v16, v16, v20
	v_mul_hi_i32_i24_e32 v21, 0x8800, v26
	v_mul_i32_i24_e32 v20, 0x8800, v26
	v_cvt_pk_bf16_f32 v12, v12, v13
	v_mul_f32_e32 v13, v19, v28
	v_mul_f32_e32 v14, v27, v29
	v_lshlrev_b64 v[20:21], 1, v[20:21]
	v_cvt_pk_bf16_f32 v13, v13, v14
	v_mul_f32_e32 v14, v51, v42
	v_mul_f32_e32 v15, v52, v55
	v_lshl_add_u64 v[22:23], s[6:7], 0, v[20:21]
	v_readlane_b32 s6, v254, 8
	v_cvt_pk_bf16_f32 v14, v14, v15
	v_mul_f32_e32 v15, v53, v54
	v_lshl_add_u64 v[22:23], v[22:23], 0, v[24:25]
	v_readlane_b32 s7, v254, 9
	v_cvt_pk_bf16_f32 v15, v15, v16
	v_cvt_pk_bf16_f32 v16, v44, v45
	v_cvt_pk_bf16_f32 v17, v46, v47
	v_cvt_pk_bf16_f32 v18, v48, v49
	v_cvt_pk_bf16_f32 v19, v50, v43
	global_store_dwordx4 v[22:23], v[12:15], off
	s_nop 1
	v_lshl_add_u64 v[12:13], s[6:7], 0, v[20:21]
	v_lshl_add_u64 v[12:13], v[12:13], 0, v[24:25]
	global_store_dwordx4 v[12:13], v[16:19], off
	s_and_saveexec_b64 s[6:7], vcc
	s_cbranch_execz .LBB0_1392
; DEVI unsigned pk_bf16(float lo, float hi) { unsigned r; asm volatile("v_cvt_pk_bf16_f32 %0, %1, %2" : "=v"(r) : "v"(lo), "v"(hi)); return r; }
; DEVI float bf2f(u16 h) { return __uint_as_float(((unsigned)h) << 16); }
; DEVI void uprep_phase(const Params& p, int l) {
;     ...
;   auto fin = [&](const In& q, const int idx) {
;     const int c = idx / NCH, ck = idx % NCH, row = ck * 8;
;     float o[3][8];
; #pragma unroll
;     for (int k = 0; k < 3; ++k) {
;       const int col = k * 256 + c;
;       float x[10];
;       x[0] = bf2f(q.pv[k]); x[9] = bf2f(q.nx[k]);
; #pragma unroll
;       for (int e = 0; e < 8; ++e) x[e + 1] = bf2f((u16)q.v[k][e]);
;       const float w0 = p.in[18][(l * 3 + 0) * 768 + col], w1 = p.in[18][(l * 3 + 1) * 768 + col], w2 = p.in[18][(l * 3 + 2) * 768 + col], bb = p.in[19][l * 768 + col];
; #pragma unroll
;       for (int e = 0; e < 8; ++e) o[k][e] = bb + w0 * x[e] + w1 * x[e + 1] + w2 * x[e + 2];
;     }
;     uint4 uo, xo;
;     uo.x = pk_bf16(o[1][0] * o[2][0], o[1][1] * o[2][1]); uo.y = pk_bf16(o[1][2] * o[2][2], o[1][3] * o[2][3]);
;     uo.z = pk_bf16(o[1][4] * o[2][4], o[1][5] * o[2][5]); uo.w = pk_bf16(o[1][6] * o[2][6], o[1][7] * o[2][7]);
;     xo.x = pk_bf16(o[0][0], o[0][1]); xo.y = pk_bf16(o[0][2], o[0][3]); xo.z = pk_bf16(o[0][4], o[0][5]); xo.w = pk_bf16(o[0][6], o[0][7]);
;     *(uint4*)(UT + (size_t)c * T + row) = uo;
;     *(uint4*)(X0T + (size_t)c * T + row) = xo;
	v_add_u32_e32 v12, v40, v39
	v_add_u32_e32 v14, s0, v12
	v_readlane_b32 s36, v252, 46
	v_ashrrev_i32_e32 v15, 31, v14
	v_readlane_b32 s40, v252, 50
	v_readlane_b32 s41, v252, 51
	v_readlane_b32 s42, v252, 52
	v_readlane_b32 s43, v252, 53
	v_lshl_add_u64 v[18:19], v[14:15], 2, s[40:41]
	v_add_u32_e32 v14, s2, v14
	v_ashrrev_i32_e32 v15, 31, v14
	v_add_u32_e32 v16, s1, v12
	v_lshl_add_u64 v[14:15], v[14:15], 2, s[42:43]
	v_mov_b32_e32 v40, v86
	v_mov_b32_e32 v41, v87
	v_ashrrev_i32_e32 v17, 31, v16
	v_mov_b32_e32 v20, v88
	v_lshl_add_u64 v[16:17], v[16:17], 2, s[40:41]
	v_mov_b32_e32 v42, v89
	v_mov_b32_e32 v49, v90
	v_lshlrev_b32_e32 v13, 16, v32
	v_lshlrev_b32_e32 v22, 16, v0
	v_and_b32_e32 v23, 0xffff0000, v0
	v_lshlrev_b32_e32 v24, 16, v1
	v_and_b32_e32 v25, 0xffff0000, v1
	v_lshlrev_b32_e32 v26, 16, v2
	v_and_b32_e32 v27, 0xffff0000, v2
	v_lshlrev_b32_e32 v29, 16, v3
	v_and_b32_e32 v39, 0xffff0000, v3
	v_lshlrev_b32_e32 v28, 16, v33
	v_and_b32_e32 v43, 0xffff0000, v5
	v_lshlrev_b32_e32 v45, 16, v6
	v_and_b32_e32 v46, 0xffff0000, v6
	v_lshlrev_b32_e32 v47, 16, v7
	v_and_b32_e32 v48, 0xffff0000, v7
	v_lshlrev_b32_e32 v53, 16, v36
	v_lshlrev_b32_e32 v44, 16, v35
	v_lshlrev_b32_e32 v52, 16, v8
	v_readlane_b32 s8, v254, 6
	v_readlane_b32 s9, v254, 7
	v_readlane_b32 s37, v252, 47
	v_readlane_b32 s38, v252, 48
	v_readlane_b32 s39, v252, 49
	v_readlane_b32 s44, v252, 54
	v_readlane_b32 s45, v252, 55
	v_readlane_b32 s46, v252, 56
	v_readlane_b32 s47, v252, 57
	v_readlane_b32 s48, v252, 58
	v_readlane_b32 s49, v252, 59
	v_readlane_b32 s50, v252, 60
	v_readlane_b32 s51, v252, 61
	s_waitcnt vmcnt(2)
	v_fma_f32 v21, v40, v13, v20
	v_fmac_f32_e32 v21, v41, v22
	v_fma_f32 v22, v40, v22, v20
	s_waitcnt vmcnt(1)
	v_fmac_f32_e32 v21, v42, v23
	v_fmac_f32_e32 v22, v41, v23
	v_fma_f32 v23, v40, v23, v20
	v_fmac_f32_e32 v22, v42, v24
	v_fmac_f32_e32 v23, v41, v24
	v_fma_f32 v24, v40, v24, v20
	v_fmac_f32_e32 v23, v42, v25
	v_fmac_f32_e32 v24, v41, v25
	v_fma_f32 v25, v40, v25, v20
	v_fmac_f32_e32 v24, v42, v26
	v_fmac_f32_e32 v25, v41, v26
	v_fma_f32 v26, v40, v26, v20
	v_fmac_f32_e32 v25, v42, v27
	v_fmac_f32_e32 v26, v41, v27
	v_fma_f32 v27, v40, v27, v20
	v_fmac_f32_e32 v20, v40, v29
	v_fmac_f32_e32 v20, v41, v39
	v_ashrrev_i32_e32 v13, 31, v12
	v_fmac_f32_e32 v26, v42, v29
	v_fmac_f32_e32 v27, v41, v29
	v_fmac_f32_e32 v20, v42, v28
	v_lshl_add_u64 v[28:29], v[12:13], 0, s[10:11]
	v_lshl_add_u64 v[54:55], v[28:29], 2, s[40:41]
	v_mov_b32_e32 v50, v91
	v_mov_b32_e32 v51, v92
	v_mov_b32_e32 v13, v93
	s_nop 0
	v_mov_b32_e32 v19, v94
	s_nop 0
	v_mov_b32_e32 v18, v95
	s_nop 0
	v_mov_b32_e32 v16, v96
	s_nop 0
	v_mov_b32_e32 v17, v97
	v_fmac_f32_e32 v27, v42, v39
	v_lshlrev_b32_e32 v39, 16, v34
	v_lshlrev_b32_e32 v40, 16, v4
	v_and_b32_e32 v41, 0xffff0000, v4
	v_lshlrev_b32_e32 v42, 16, v5
	s_waitcnt vmcnt(4)
	v_fma_f32 v28, v49, v39, v13
	v_fma_f32 v29, v49, v40, v13
	v_fma_f32 v39, v49, v41, v13
	v_fmac_f32_e32 v28, v50, v40
	v_fmac_f32_e32 v29, v50, v41
	v_fmac_f32_e32 v39, v50, v42
	v_fma_f32 v40, v49, v42, v13
	v_fmac_f32_e32 v28, v51, v41
	v_fmac_f32_e32 v29, v51, v42
	v_fmac_f32_e32 v39, v51, v43
	v_fmac_f32_e32 v40, v50, v43
	v_fma_f32 v41, v49, v43, v13
	v_fma_f32 v42, v49, v45, v13
	v_fma_f32 v43, v49, v46, v13
	v_fmac_f32_e32 v13, v49, v47
	v_fmac_f32_e32 v41, v50, v45
	v_fmac_f32_e32 v42, v50, v46
	v_fmac_f32_e32 v43, v50, v47
	v_fmac_f32_e32 v13, v50, v48
	s_waitcnt vmcnt(0)
	v_fma_f32 v14, v19, v53, v17
	v_fmac_f32_e32 v40, v51, v45
	v_fmac_f32_e32 v41, v51, v46
	v_fmac_f32_e32 v42, v51, v47
	v_fmac_f32_e32 v43, v51, v48
	v_fmac_f32_e32 v13, v51, v44
	v_and_b32_e32 v51, 0xffff0000, v8
	v_fmac_f32_e32 v14, v18, v52
	v_fma_f32 v15, v19, v52, v17
	v_lshlrev_b32_e32 v50, 16, v9
	v_fmac_f32_e32 v14, v16, v51
	v_fmac_f32_e32 v15, v18, v51
	v_fma_f32 v51, v19, v51, v17
	v_and_b32_e32 v49, 0xffff0000, v9
	v_fmac_f32_e32 v15, v16, v50
	v_fmac_f32_e32 v51, v18, v50
	v_fma_f32 v50, v19, v50, v17
	v_lshlrev_b32_e32 v48, 16, v10
	v_fmac_f32_e32 v51, v16, v49
	v_fmac_f32_e32 v50, v18, v49
	v_fma_f32 v49, v19, v49, v17
	v_and_b32_e32 v47, 0xffff0000, v10
	v_lshlrev_b32_e32 v46, 16, v11
	v_fmac_f32_e32 v50, v16, v48
	v_fmac_f32_e32 v49, v18, v48
	v_fma_f32 v48, v19, v48, v17
	v_and_b32_e32 v45, 0xffff0000, v11
	v_fmac_f32_e32 v49, v16, v47
	v_fmac_f32_e32 v48, v18, v47
	v_fma_f32 v47, v19, v47, v17
	v_fmac_f32_e32 v17, v19, v46
	v_lshlrev_b32_e32 v44, 16, v37
	v_fmac_f32_e32 v47, v18, v46
	v_fmac_f32_e32 v17, v18, v45
	v_fmac_f32_e32 v48, v16, v46
	v_fmac_f32_e32 v47, v16, v45
	v_fmac_f32_e32 v17, v16, v44
	v_mul_i32_i24_e32 v16, 0x1100, v12
	v_sub_u32_e32 v16, v38, v16
	v_mul_f32_e32 v14, v28, v14
	v_mul_f32_e32 v15, v29, v15
	v_lshlrev_b32_e32 v18, 3, v16
	v_cvt_pk_bf16_f32 v14, v14, v15
	v_mul_f32_e32 v15, v39, v51
	v_mul_f32_e32 v16, v40, v50
	v_cvt_pk_bf16_f32 v15, v15, v16
	v_mul_f32_e32 v16, v41, v49
	v_mul_f32_e32 v19, v42, v48
	v_mul_f32_e32 v13, v13, v17
	v_cvt_pk_bf16_f32 v16, v16, v19
	v_mul_f32_e32 v19, v43, v47
	v_cvt_pk_bf16_f32 v17, v19, v13
	v_mul_hi_i32_i24_e32 v13, 0x8800, v12
	v_mul_i32_i24_e32 v12, 0x8800, v12
	v_lshlrev_b64 v[12:13], 1, v[12:13]
	v_cvt_pk_bf16_f32 v22, v21, v22
	v_cvt_pk_bf16_f32 v23, v23, v24
	v_cvt_pk_bf16_f32 v24, v25, v26
	v_cvt_pk_bf16_f32 v25, v27, v20
	v_lshl_add_u64 v[20:21], s[8:9], 0, v[12:13]
	v_readlane_b32 s8, v254, 8
	v_ashrrev_i32_e32 v19, 31, v18
	v_readlane_b32 s9, v254, 9
	v_lshlrev_b64 v[18:19], 1, v[18:19]
	v_lshl_add_u64 v[20:21], v[20:21], 0, v[18:19]
	v_lshl_add_u64 v[12:13], s[8:9], 0, v[12:13]
	v_lshl_add_u64 v[12:13], v[12:13], 0, v[18:19]
	global_store_dwordx4 v[20:21], v[14:17], off
	global_store_dwordx4 v[12:13], v[22:25], off
	s_branch .LBB0_1392
